# v104 = v102 + one static s_setprio 1 for waves 4-7 over the attention phase (reset at phase exit)
# baseline (speedup 1.0000x reference)
; __global__ void __launch_bounds__(NWAVES * 64, 2) mega_fwd(Args args) {
;     ...
;     if (IN(2)) {
;         const bool lv = (F.MISC[11] == 1u) && F.G == 256 && IN(0) && IN(1);
;         const int vcu2 = lv ? (int)bar.x * 32 + (int)F.MISC[10] : F.vcu;
;         dattn::Seam S; dattn::BlockRef cur = mk_block(P, vcu2, 0);
;         if (F.G == 256) dattn::dattn_issue(cur, (char*)lds + RING_OFF, S);
.LBB0_315:
	s_cmp_lt_i32 s52, 3
	s_cselect_b64 s[0:1], -1, 0
	s_cmp_gt_i32 s53, 2
	s_cselect_b64 s[4:5], -1, 0
	s_and_b64 s[0:1], s[0:1], s[4:5]
	s_andn2_b64 vcc, exec, s[0:1]
	s_cbranch_vccnz .LBB0_553
	v_readfirstlane_b32 s0, v0
	s_cmpk_lt_i32 s0, 0x100
	s_cbranch_scc1 .Lp2prio_lo
	s_setprio 1
.Lp2prio_lo:
	s_add_i32 s0, 0, 0x27d6c
	v_mov_b32_e32 v1, s0
	ds_read_b32 v1, v1
	v_readlane_b32 s4, v236, 2
	v_readlane_b32 s5, v236, 3
	s_waitcnt lgkmcnt(0)
	v_readfirstlane_b32 s0, v1
	s_cmp_eq_u32 s0, 1
	s_cselect_b64 s[0:1], -1, 0
	s_cmpk_eq_i32 s3, 0x100
	s_cselect_b64 s[10:11], -1, 0
	s_and_b64 s[0:1], s[10:11], s[0:1]
	s_and_b64 s[0:1], s[4:5], s[0:1]
	s_xor_b64 s[6:7], s[0:1], -1
	s_and_b64 vcc, exec, s[6:7]
	s_mov_b32 s0, s2
	s_cbranch_vccnz .LBB0_318
	s_add_i32 s0, 0, 0x27d68
	v_mov_b32_e32 v1, s0
	ds_read_b32 v1, v1
	s_lshl_b32 s0, s72, 5
	s_waitcnt lgkmcnt(0)
	v_readfirstlane_b32 s1, v1
	s_add_i32 s0, s1, s0

; #define STAMP(k) do { if (blockIdx.x == 0 && F.tid == 0) { const unsigned long long t_ = rt(); F.MISC[16 + 2 * (k)] = (unsigned)t_; F.MISC[17 + 2 * (k)] = (unsigned)(t_ >> 32); } } while (0)
; #define STAMP(k) do { } while (0)
; __global__ void __launch_bounds__(NWAVES * 64, 2) mega_fwd(Args args) {
;     ...
;     STAMP(3);
;     if (IN(3)) {
;         const bool lv = (F.MISC[11] == 1u) && F.G == 256 && IN(0) && IN(1) && IN(2);
;         pg8::Gemm g{(const bf16*)(P.ws + WS_BR), (const bf16*)(P.ws + WS_WBR), MROWS, DM, DM}; pg8::XcdOrder S; S.so.init(MROWS, DM, F.G, (int)blockIdx.x); S.local = lv ? (args.li == 0 ? 2 : 1) : 0; S.xcc = (int)bar.x; S.rank = (int)F.MISC[10];
.LBB0_553:
	s_setprio 0
	s_cmp_lt_i32 s52, 4
	s_cselect_b64 s[0:1], -1, 0
	s_cmp_gt_i32 s53, 3
	s_cselect_b64 s[4:5], -1, 0
	s_and_b64 s[0:1], s[0:1], s[4:5]
	s_andn2_b64 vcc, exec, s[0:1]
	s_cbranch_vccnz .LBB0_688
	s_add_i32 s0, 0, 0x27d6c
	v_mov_b32_e32 v1, s0
	ds_read_b32 v1, v1
	s_mov_b64 s[8:9], -1
	s_waitcnt lgkmcnt(0)
	v_readfirstlane_b32 s24, v0
	v_readfirstlane_b32 s0, v1
	s_cmp_eq_u32 s0, 1
	s_cselect_b64 s[0:1], -1, 0
	s_cmpk_eq_i32 s3, 0x100
	s_cselect_b64 s[4:5], -1, 0
	s_and_b64 s[0:1], s[4:5], s[0:1]
	v_readlane_b32 s4, v236, 2
	v_readlane_b32 s5, v236, 3
	s_and_b64 s[4:5], s[4:5], s[0:1]
	s_cmp_eq_u32 s54, 0
	s_cselect_b64 s[6:7], -1, 0
	s_cmp_lg_u32 s54, 0
	s_cselect_b64 s[0:1], -1, 0
	s_add_i32 s2, 0, 0x27d68
	v_mov_b32_e32 v1, s2
	ds_read_b32 v1, v1
	s_and_b64 vcc, exec, s[4:5]
	s_waitcnt lgkmcnt(0)
	v_readfirstlane_b32 s26, v1
	s_cbranch_vccnz .LBB0_559
	s_mov_b64 s[8:9], 0
	s_cmpk_lt_i32 s98, 0x200
	s_mov_b64 s[10:11], 0
	s_cbranch_scc1 .LBB0_560
	s_and_b64 vcc, exec, s[8:9]
	s_cbranch_vccnz .LBB0_565
